# E61: prompt-FoX loop: next-tile K/V addresses kept in registers and advanced by the tile stride (4 VALU instead of 14) plus row-max tree without self-max canonicalisation (8 VALU fewer); on E41
# speedup vs baseline: 1.0374x; 1.0040x over previous
.LBB0_1387:
	s_or_b64 exec, exec, s[18:19]
	s_movk_i32 s15, 0x90
	v_mul_lo_u32 v147, v4, s15
	v_lshlrev_b32_e32 v153, 4, v8
	v_add3_u32 v8, 0, v147, v153
	s_waitcnt lgkmcnt(0)
	s_barrier
	s_barrier
	ds_write_b128 v8, v[130:133]
	v_mad_u64_u32 v[8:9], s[16:17], v4, 48, v[8:9]
	v_mul_lo_u32 v174, v6, s15
	v_lshlrev_b32_e32 v175, 4, v5
	ds_write_b128 v8, v[134:137] offset:18432
	v_add3_u32 v8, 0, v174, v175
	v_lshrrev_b32_e32 v2, 2, v2
	s_cmp_lt_i32 s13, s12
	s_movk_i32 s18, 0xc0
	ds_write_b128 v8, v[138:141]
	v_mad_u64_u32 v[8:9], s[16:17], v6, 48, v[8:9]
	v_and_or_b32 v5, v2, 3, v216
	v_and_or_b32 v2, v2, 4, v225
	v_mov_b32_e32 v16, v3
	v_mov_b32_e32 v17, v3
	s_cselect_b64 s[84:85], -1, 0
	s_add_i32 s14, s9, 0x7f
	s_add_i32 s13, s13, s8
	v_mul_lo_u32 v173, v4, s18
	v_mul_lo_u32 v191, v6, s18
	ds_write_b128 v8, v[142:145] offset:18432
	v_lshlrev_b32_e32 v193, 3, v2
	v_mul_u32_u24_e32 v194, 0xc0, v5
	v_add_u32_e32 v196, 0x80, v6
	v_add_u32_e32 v197, 0x80, v4
	v_mov_b32_e32 v2, v3
	v_mov_b32_e32 v4, v3
	v_mov_b32_e32 v5, v3
	v_mov_b32_e32 v6, v3
	v_mov_b32_e32 v7, v3
	v_mov_b32_e32 v8, v3
	v_mov_b32_e32 v9, v3
	v_mov_b32_e32 v10, v3
	v_mov_b32_e32 v11, v3
	v_mov_b32_e32 v12, v3
	v_mov_b32_e32 v13, v3
	v_mov_b32_e32 v14, v3
	v_mov_b32_e32 v15, v3
	v_mov_b64_e32 v[32:33], v[16:17]
	v_mov_b64_e32 v[48:49], v[16:17]
	s_lshr_b32 s14, s14, 7
	s_movk_i32 s72, 0x90
	s_movk_i32 s73, 0xc0
	s_add_i32 s15, s13, 31
	v_add_u32_e32 v195, s13, v188
	s_mov_b32 s16, 0
	v_mov_b32_e32 v158, 0xf149f2ca
	v_mov_b32_e32 v192, 0
	v_mov_b32_e32 v198, v187
	v_mov_b64_e32 v[30:31], v[14:15]
	v_mov_b64_e32 v[28:29], v[12:13]
	v_mov_b64_e32 v[26:27], v[10:11]
	v_mov_b64_e32 v[24:25], v[8:9]
	v_mov_b64_e32 v[22:23], v[6:7]
	v_mov_b64_e32 v[20:21], v[4:5]
	v_mov_b64_e32 v[18:19], v[2:3]
	v_mov_b64_e32 v[46:47], v[14:15]
	v_mov_b64_e32 v[44:45], v[12:13]
	v_mov_b64_e32 v[42:43], v[10:11]
	v_mov_b64_e32 v[40:41], v[8:9]
	v_mov_b64_e32 v[38:39], v[6:7]
	v_mov_b64_e32 v[36:37], v[4:5]
	v_mov_b64_e32 v[34:35], v[2:3]
	s_mov_b32 s18, 0
	s_waitcnt lgkmcnt(0)
	s_barrier
	v_mov_b32_e32 v4, v197
	v_ashrrev_i32_e32 v5, 31, v4
	v_lshlrev_b64 v[4:5], 9, v[4:5]
	v_lshl_add_u64 v[4:5], v[4:5], 0, v[148:149]
	v_lshlrev_b64 v[4:5], 1, v[4:5]
	v_lshl_add_u64 v[248:249], s[64:65], 0, v[4:5]
	v_lshl_add_u64 v[246:247], s[66:67], 0, v[4:5]
	v_mov_b32_e32 v4, v196
	v_ashrrev_i32_e32 v5, 31, v4
	v_lshlrev_b64 v[4:5], 9, v[4:5]
	v_lshl_add_u64 v[4:5], v[4:5], 0, v[156:157]
	v_lshlrev_b64 v[4:5], 1, v[4:5]
	v_lshl_add_u64 v[250:251], s[64:65], 0, v[4:5]
	v_lshl_add_u64 v[252:253], s[66:67], 0, v[4:5]
	s_mov_b32 s100, 0x20000
	s_mov_b32 s101, 0
.LBB0_1388:
	s_add_i32 s17, s18, 1
	s_cmp_lt_u32 s17, s14
	s_cselect_b64 s[90:91], -1, 0
	s_cmp_ge_u32 s17, s14
	s_cbranch_scc1 .LBB0_1390
	global_load_dwordx4 v[134:137], v[246:247], off
	global_load_dwordx4 v[130:133], v[248:249], off
	global_load_dwordx4 v[138:141], v[250:251], off
	global_load_dwordx4 v[142:145], v[252:253], off
	v_lshl_add_u64 v[246:247], v[246:247], 0, s[100:101]
	v_lshl_add_u64 v[248:249], v[248:249], 0, s[100:101]
	v_lshl_add_u64 v[250:251], v[250:251], 0, s[100:101]
	v_lshl_add_u64 v[252:253], v[252:253], 0, s[100:101]
